# tile loop: group-size division replaced by shift/mask (gsz is always 8), trailing half's restore barrier moved after its tile-header computation
# speedup vs baseline: 1.0086x; 1.0086x over previous
.LBB0_287:
	s_add_i32 s19, s19, 1
	v_readlane_b32 s0, v252, 61
	s_mul_i32 s0, s19, s0
	s_mul_hi_u32 s1, s19, s98
	s_add_i32 s1, s1, s0
	s_mul_i32 s0, s19, s98
	v_readlane_b32 s11, v252, 0
	s_add_u32 s12, s0, s11
	v_readlane_b32 s0, v252, 58
	s_addc_u32 s13, s1, s0
	s_waitcnt lgkmcnt(0)
	v_mov_b64_e32 v[0:1], s[64:65]
	v_cmp_ge_i64_e32 vcc, s[12:13], v[0:1]
	v_cmp_lt_i64_e64 s[0:1], s[12:13], v[0:1]
	s_cbranch_vccnz .LBB0_289
	s_ashr_i32 s11, s12, 31
	s_lshr_b32 s11, s11, 29
	s_add_i32 s11, s12, s11
	s_ashr_i32 s13, s11, 3
	s_and_b32 s11, s11, -8
	s_sub_i32 s11, s12, s11
	s_lshr_b32 s12, s11, 31
	v_readlane_b32 s6, v255, 41
	s_or_b32 s12, s6, s12
	s_mul_i32 s11, s12, s11
	s_add_i32 s11, s11, s13
	s_ashr_i32 s12, s11, 31
	v_readlane_b32 s6, v255, 48
	s_xor_b32 s12, s12, s6
	s_abs_i32 s13, s11
	v_readlane_b32 s6, v255, 49
	s_mul_hi_u32 s22, s13, s6
	s_mul_i32 s23, s22, s27
	s_sub_i32 s13, s13, s23
	s_add_i32 s23, s22, 1
	s_sub_i32 s24, s13, s27
	s_cmp_ge_u32 s13, s27
	s_cselect_b32 s22, s23, s22
	s_cselect_b32 s13, s24, s13
	s_add_i32 s23, s22, 1
	s_cmp_ge_u32 s13, s27
	s_cselect_b32 s13, s23, s22
	s_xor_b32 s13, s13, s12
	s_sub_i32 s12, s13, s12
	s_lshl_b32 s13, s12, 3
	s_mul_i32 s12, s12, s41
	s_sub_i32 s11, s11, s12
	s_lshr_b32 s59, s11, 3
	s_and_b32 s11, s11, 7
	s_add_i32 s54, s11, s13

.LBB0_293:
	v_readlane_b32 s0, v255, 31
	v_readlane_b32 s1, v255, 32
	s_andn2_b64 vcc, exec, s[0:1]
	s_cbranch_vccnz .LBB0_296
	s_cmp_lt_u32 s19, 2
	s_cbranch_scc1 .Lno_restore
	v_readlane_b32 s82, v255, 33
	s_cmp_lg_u32 s82, 0
	s_cbranch_scc1 .Lno_restore
	s_barrier
.Lno_restore:
	s_add_u32 s0, s90, 0x80
	s_addc_u32 s1, s91, 0
	s_add_u32 s11, s2, 0x100
	s_addc_u32 s24, s3, 0
	s_mov_b32 s2, 0
	s_add_i32 s90, s2, 2
	s_add_u32 s82, s0, 0x80
	s_addc_u32 s3, s1, 0
	s_add_i32 s83, 0, 0x10000
	s_cmp_eq_u32 s62, s2
	s_cselect_b32 s3, s23, s3
	s_cselect_b32 s2, s22, s82
	s_cselect_b32 vcc_hi, s13, s24
	s_cselect_b32 vcc_lo, s12, s11
	s_add_i32 s82, 0, 0x14000
	v_add_u32_e32 v140, s83, v157
	v_add_u32_e32 v144, s82, v157
	ds_read_b128 v[128:131], v140
	ds_read_b128 v[132:135], v140 offset:1024
	ds_read_b128 v[136:139], v140 offset:2048
	ds_read_b128 v[140:143], v140 offset:3072
	ds_read_b128 v[166:169], v144
	ds_read_b128 v[176:179], v144 offset:1024
	ds_read_b128 v[180:183], v144 offset:2048
	ds_read_b128 v[184:187], v144 offset:3072
	v_lshl_add_u64 v[170:171], s[0:1], 0, v[160:161]
	s_add_i32 m0, s37, 0xc000
	ds_read_b128 v[188:191], v242
	ds_read_b128 v[192:195], v242 offset:1024
	ds_read_b128 v[196:199], v242 offset:2048
	ds_read_b128 v[200:203], v242 offset:3072
	ds_read_b128 v[204:207], v242 offset:4096
	ds_read_b128 v[208:211], v242 offset:5120
	ds_read_b128 v[212:215], v242 offset:6144
	ds_read_b128 v[216:219], v242 offset:7168
	global_load_lds_dwordx4 v[170:171], off
	v_lshl_add_u64 v[170:171], s[0:1], 0, v[162:163]
	s_add_i32 m0, s37, 0xe000
	s_nop 0
	global_load_lds_dwordx4 v[170:171], off
	s_waitcnt vmcnt(8) lgkmcnt(0)
	s_barrier
	s_setprio 1
	v_mfma_f32_16x16x32_bf16 v[124:127], v[128:131], v[188:191], 0
	v_mfma_f32_16x16x32_bf16 v[120:123], v[136:139], v[188:191], 0
	v_mfma_f32_16x16x32_bf16 v[108:111], v[128:131], v[196:199], 0
	v_mfma_f32_16x16x32_bf16 v[104:107], v[136:139], v[196:199], 0
	v_mfma_f32_16x16x32_bf16 v[92:95], v[128:131], v[204:207], 0
	v_mfma_f32_16x16x32_bf16 v[88:91], v[136:139], v[204:207], 0
	v_mfma_f32_16x16x32_bf16 v[76:79], v[128:131], v[212:215], 0
	v_mfma_f32_16x16x32_bf16 v[72:75], v[136:139], v[212:215], 0
	v_mfma_f32_16x16x32_bf16 v[124:127], v[132:135], v[192:195], v[124:127]
	v_mfma_f32_16x16x32_bf16 v[120:123], v[140:143], v[192:195], v[120:123]
	v_mfma_f32_16x16x32_bf16 v[108:111], v[132:135], v[200:203], v[108:111]
	v_mfma_f32_16x16x32_bf16 v[104:107], v[140:143], v[200:203], v[104:107]
	v_mfma_f32_16x16x32_bf16 v[92:95], v[132:135], v[208:211], v[92:95]
	v_mfma_f32_16x16x32_bf16 v[88:91], v[140:143], v[208:211], v[88:91]
	v_mfma_f32_16x16x32_bf16 v[76:79], v[132:135], v[216:219], v[76:79]
	v_mfma_f32_16x16x32_bf16 v[72:75], v[140:143], v[216:219], v[72:75]
	s_setprio 0
	s_setprio 1
	v_mfma_f32_16x16x32_bf16 v[116:119], v[166:169], v[188:191], 0
	v_mfma_f32_16x16x32_bf16 v[112:115], v[180:183], v[188:191], 0
	v_mfma_f32_16x16x32_bf16 v[100:103], v[166:169], v[196:199], 0
	v_mfma_f32_16x16x32_bf16 v[96:99], v[180:183], v[196:199], 0
	v_mfma_f32_16x16x32_bf16 v[84:87], v[166:169], v[204:207], 0
	v_mfma_f32_16x16x32_bf16 v[80:83], v[180:183], v[204:207], 0
	v_mfma_f32_16x16x32_bf16 v[68:71], v[166:169], v[212:215], 0
	v_mfma_f32_16x16x32_bf16 v[64:67], v[180:183], v[212:215], 0
	v_mfma_f32_16x16x32_bf16 v[116:119], v[176:179], v[192:195], v[116:119]
	v_mfma_f32_16x16x32_bf16 v[112:115], v[184:187], v[192:195], v[112:115]
	v_mfma_f32_16x16x32_bf16 v[100:103], v[176:179], v[200:203], v[100:103]
	v_mfma_f32_16x16x32_bf16 v[96:99], v[184:187], v[200:203], v[96:99]
	v_mfma_f32_16x16x32_bf16 v[84:87], v[176:179], v[208:211], v[84:87]
	v_mfma_f32_16x16x32_bf16 v[80:83], v[184:187], v[208:211], v[80:83]
	v_mfma_f32_16x16x32_bf16 v[68:71], v[176:179], v[216:219], v[68:71]
	v_mfma_f32_16x16x32_bf16 v[64:67], v[184:187], v[216:219], v[64:67]
	s_setprio 0
	s_barrier
	s_add_i32 s83, s83, s36
	v_lshl_add_u64 v[170:171], vcc, 0, v[150:151]
	s_mov_b32 m0, s83
	ds_read_b128 v[188:191], v242 offset:16384
	ds_read_b128 v[192:195], v242 offset:17408
	ds_read_b128 v[196:199], v242 offset:18432
	ds_read_b128 v[200:203], v242 offset:19456
	ds_read_b128 v[204:207], v242 offset:20480
	ds_read_b128 v[208:211], v242 offset:21504
	ds_read_b128 v[212:215], v242 offset:22528
	ds_read_b128 v[216:219], v242 offset:23552
	global_load_lds_dwordx4 v[170:171], off
	s_add_i32 m0, s83, 0x2000
	v_lshl_add_u64 v[232:233], vcc, 0, v[154:155]
	s_add_u32 vcc_lo, vcc_lo, s26
	s_addc_u32 vcc_hi, vcc_hi, 0
	s_add_i32 s82, s82, s36
	global_load_lds_dwordx4 v[232:233], off
	v_lshl_add_u64 v[234:235], vcc, 0, v[150:151]
	s_mov_b32 m0, s82
	v_lshl_add_u64 v[246:247], vcc, 0, v[154:155]
	global_load_lds_dwordx4 v[234:235], off
	s_add_i32 m0, s82, 0x2000
	v_lshl_add_u64 v[248:249], s[2:3], 0, v[148:149]
	global_load_lds_dwordx4 v[246:247], off
	s_mov_b32 m0, s37
	v_lshl_add_u64 v[250:251], s[2:3], 0, v[152:153]
	global_load_lds_dwordx4 v[248:249], off
	s_mov_b32 m0, s42
	s_nop 0
	global_load_lds_dwordx4 v[250:251], off
	s_waitcnt vmcnt(8) lgkmcnt(0)
	s_barrier
	s_setprio 1
	v_mfma_f32_16x16x32_bf16 v[60:63], v[128:131], v[188:191], 0
	v_mfma_f32_16x16x32_bf16 v[56:59], v[136:139], v[188:191], 0
	v_mfma_f32_16x16x32_bf16 v[44:47], v[128:131], v[196:199], 0
	v_mfma_f32_16x16x32_bf16 v[40:43], v[136:139], v[196:199], 0
	v_mfma_f32_16x16x32_bf16 v[28:31], v[128:131], v[204:207], 0
	v_mfma_f32_16x16x32_bf16 v[24:27], v[136:139], v[204:207], 0
	v_mfma_f32_16x16x32_bf16 v[12:15], v[128:131], v[212:215], 0
	v_mfma_f32_16x16x32_bf16 v[8:11], v[136:139], v[212:215], 0
	v_mfma_f32_16x16x32_bf16 v[60:63], v[132:135], v[192:195], v[60:63]
	v_mfma_f32_16x16x32_bf16 v[56:59], v[140:143], v[192:195], v[56:59]
	v_mfma_f32_16x16x32_bf16 v[44:47], v[132:135], v[200:203], v[44:47]
	v_mfma_f32_16x16x32_bf16 v[40:43], v[140:143], v[200:203], v[40:43]
	v_mfma_f32_16x16x32_bf16 v[28:31], v[132:135], v[208:211], v[28:31]
	v_mfma_f32_16x16x32_bf16 v[24:27], v[140:143], v[208:211], v[24:27]
	v_mfma_f32_16x16x32_bf16 v[12:15], v[132:135], v[216:219], v[12:15]
	v_mfma_f32_16x16x32_bf16 v[8:11], v[140:143], v[216:219], v[8:11]
	s_setprio 0
	s_setprio 1
	v_mfma_f32_16x16x32_bf16 v[52:55], v[166:169], v[188:191], 0
	v_mfma_f32_16x16x32_bf16 v[48:51], v[180:183], v[188:191], 0
	v_mfma_f32_16x16x32_bf16 v[36:39], v[166:169], v[196:199], 0
	v_mfma_f32_16x16x32_bf16 v[32:35], v[180:183], v[196:199], 0
	v_mfma_f32_16x16x32_bf16 v[20:23], v[166:169], v[204:207], 0
	v_mfma_f32_16x16x32_bf16 v[16:19], v[180:183], v[204:207], 0
	v_mfma_f32_16x16x32_bf16 v[4:7], v[166:169], v[212:215], 0
	v_mfma_f32_16x16x32_bf16 v[0:3], v[180:183], v[212:215], 0
	v_mfma_f32_16x16x32_bf16 v[52:55], v[176:179], v[192:195], v[52:55]
	v_mfma_f32_16x16x32_bf16 v[48:51], v[184:187], v[192:195], v[48:51]
	v_mfma_f32_16x16x32_bf16 v[36:39], v[176:179], v[200:203], v[36:39]
	v_mfma_f32_16x16x32_bf16 v[32:35], v[184:187], v[200:203], v[32:35]
	v_mfma_f32_16x16x32_bf16 v[20:23], v[176:179], v[208:211], v[20:23]
	v_mfma_f32_16x16x32_bf16 v[16:19], v[184:187], v[208:211], v[16:19]
	v_mfma_f32_16x16x32_bf16 v[4:7], v[176:179], v[216:219], v[4:7]
	v_mfma_f32_16x16x32_bf16 v[0:3], v[184:187], v[216:219], v[0:3]
	s_setprio 0
	s_barrier
	s_add_i32 s82, 0, 0x18000
	s_add_i32 s83, 0, 0x1c000
	v_add_u32_e32 v140, s82, v157
	v_add_u32_e32 v144, s83, v157
	ds_read_b128 v[128:131], v140
	ds_read_b128 v[132:135], v140 offset:1024
	ds_read_b128 v[136:139], v140 offset:2048
	ds_read_b128 v[140:143], v140 offset:3072
	ds_read_b128 v[166:169], v144
	ds_read_b128 v[176:179], v144 offset:1024
	ds_read_b128 v[180:183], v144 offset:2048
	ds_read_b128 v[184:187], v144 offset:3072
	s_add_u32 s2, s2, s58
	s_addc_u32 s3, s3, 0
	s_mov_b32 m0, s43
	v_lshl_add_u64 v[238:239], s[2:3], 0, v[148:149]
	ds_read_b128 v[188:191], v242 offset:32768
	ds_read_b128 v[192:195], v242 offset:33792
	ds_read_b128 v[196:199], v242 offset:34816
	ds_read_b128 v[200:203], v242 offset:35840
	ds_read_b128 v[204:207], v242 offset:36864
	ds_read_b128 v[208:211], v242 offset:37888
	ds_read_b128 v[212:215], v242 offset:38912
	ds_read_b128 v[216:219], v242 offset:39936
	global_load_lds_dwordx4 v[238:239], off
	v_lshl_add_u64 v[238:239], s[2:3], 0, v[152:153]
	s_mov_b32 m0, s16
	s_nop 0
	global_load_lds_dwordx4 v[238:239], off
	s_waitcnt vmcnt(8) lgkmcnt(0)
	s_barrier
	s_setprio 1
	v_mfma_f32_16x16x32_bf16 v[124:127], v[128:131], v[188:191], v[124:127]
	v_mfma_f32_16x16x32_bf16 v[120:123], v[136:139], v[188:191], v[120:123]
	v_mfma_f32_16x16x32_bf16 v[108:111], v[128:131], v[196:199], v[108:111]
	v_mfma_f32_16x16x32_bf16 v[104:107], v[136:139], v[196:199], v[104:107]
	v_mfma_f32_16x16x32_bf16 v[92:95], v[128:131], v[204:207], v[92:95]
	v_mfma_f32_16x16x32_bf16 v[88:91], v[136:139], v[204:207], v[88:91]
	v_mfma_f32_16x16x32_bf16 v[76:79], v[128:131], v[212:215], v[76:79]
	v_mfma_f32_16x16x32_bf16 v[72:75], v[136:139], v[212:215], v[72:75]
	v_mfma_f32_16x16x32_bf16 v[124:127], v[132:135], v[192:195], v[124:127]
	v_mfma_f32_16x16x32_bf16 v[120:123], v[140:143], v[192:195], v[120:123]
	v_mfma_f32_16x16x32_bf16 v[108:111], v[132:135], v[200:203], v[108:111]
	v_mfma_f32_16x16x32_bf16 v[104:107], v[140:143], v[200:203], v[104:107]
	v_mfma_f32_16x16x32_bf16 v[92:95], v[132:135], v[208:211], v[92:95]
	v_mfma_f32_16x16x32_bf16 v[88:91], v[140:143], v[208:211], v[88:91]
	v_mfma_f32_16x16x32_bf16 v[76:79], v[132:135], v[216:219], v[76:79]
	v_mfma_f32_16x16x32_bf16 v[72:75], v[140:143], v[216:219], v[72:75]
	s_setprio 0
	s_setprio 1
	v_mfma_f32_16x16x32_bf16 v[116:119], v[166:169], v[188:191], v[116:119]
	v_mfma_f32_16x16x32_bf16 v[112:115], v[180:183], v[188:191], v[112:115]
	v_mfma_f32_16x16x32_bf16 v[100:103], v[166:169], v[196:199], v[100:103]
	v_mfma_f32_16x16x32_bf16 v[96:99], v[180:183], v[196:199], v[96:99]
	v_mfma_f32_16x16x32_bf16 v[84:87], v[166:169], v[204:207], v[84:87]
	v_mfma_f32_16x16x32_bf16 v[80:83], v[180:183], v[204:207], v[80:83]
	v_mfma_f32_16x16x32_bf16 v[68:71], v[166:169], v[212:215], v[68:71]
	v_mfma_f32_16x16x32_bf16 v[64:67], v[180:183], v[212:215], v[64:67]
	v_mfma_f32_16x16x32_bf16 v[116:119], v[176:179], v[192:195], v[116:119]
	v_mfma_f32_16x16x32_bf16 v[112:115], v[184:187], v[192:195], v[112:115]
	v_mfma_f32_16x16x32_bf16 v[100:103], v[176:179], v[200:203], v[100:103]
	v_mfma_f32_16x16x32_bf16 v[96:99], v[184:187], v[200:203], v[96:99]
	v_mfma_f32_16x16x32_bf16 v[84:87], v[176:179], v[208:211], v[84:87]
	v_mfma_f32_16x16x32_bf16 v[80:83], v[184:187], v[208:211], v[80:83]
	v_mfma_f32_16x16x32_bf16 v[68:71], v[176:179], v[216:219], v[68:71]
	v_mfma_f32_16x16x32_bf16 v[64:67], v[184:187], v[216:219], v[64:67]
	s_setprio 0
	s_barrier
	s_add_i32 s2, s82, s36
	v_lshl_add_u64 v[170:171], v[170:171], 0, s[30:31]
	s_mov_b32 m0, s2
	ds_read_b128 v[188:191], v242 offset:49152
	ds_read_b128 v[192:195], v242 offset:50176
	ds_read_b128 v[196:199], v242 offset:51200
	ds_read_b128 v[200:203], v242 offset:52224
	ds_read_b128 v[204:207], v242 offset:53248
	ds_read_b128 v[208:211], v242 offset:54272
	ds_read_b128 v[212:215], v242 offset:55296
	ds_read_b128 v[216:219], v242 offset:56320
	global_load_lds_dwordx4 v[170:171], off
	v_lshl_add_u64 v[170:171], v[232:233], 0, s[30:31]
	s_add_i32 m0, s2, 0x2000
	s_add_i32 s2, s83, s36
	global_load_lds_dwordx4 v[170:171], off
	v_lshl_add_u64 v[170:171], v[234:235], 0, s[30:31]
	s_mov_b32 m0, s2
	s_nop 0
	global_load_lds_dwordx4 v[170:171], off
	v_lshl_add_u64 v[170:171], v[246:247], 0, s[30:31]
	s_add_i32 m0, s2, 0x2000
	s_nop 0
	global_load_lds_dwordx4 v[170:171], off
	v_lshl_add_u64 v[170:171], v[248:249], 0, s[30:31]
	s_mov_b32 m0, s63
	s_nop 0
	global_load_lds_dwordx4 v[170:171], off
	v_lshl_add_u64 v[170:171], v[250:251], 0, s[30:31]
	s_mov_b32 m0, s18
	s_nop 0
	global_load_lds_dwordx4 v[170:171], off
	s_waitcnt vmcnt(8) lgkmcnt(0)
	s_barrier
	s_setprio 1
	v_mfma_f32_16x16x32_bf16 v[60:63], v[128:131], v[188:191], v[60:63]
	v_mfma_f32_16x16x32_bf16 v[56:59], v[136:139], v[188:191], v[56:59]
	v_mfma_f32_16x16x32_bf16 v[44:47], v[128:131], v[196:199], v[44:47]
	v_mfma_f32_16x16x32_bf16 v[40:43], v[136:139], v[196:199], v[40:43]
	v_mfma_f32_16x16x32_bf16 v[28:31], v[128:131], v[204:207], v[28:31]
	v_mfma_f32_16x16x32_bf16 v[24:27], v[136:139], v[204:207], v[24:27]
	v_mfma_f32_16x16x32_bf16 v[12:15], v[128:131], v[212:215], v[12:15]
	v_mfma_f32_16x16x32_bf16 v[8:11], v[136:139], v[212:215], v[8:11]
	v_mfma_f32_16x16x32_bf16 v[60:63], v[132:135], v[192:195], v[60:63]
	v_mfma_f32_16x16x32_bf16 v[56:59], v[140:143], v[192:195], v[56:59]
	v_mfma_f32_16x16x32_bf16 v[44:47], v[132:135], v[200:203], v[44:47]
	v_mfma_f32_16x16x32_bf16 v[40:43], v[140:143], v[200:203], v[40:43]
	v_mfma_f32_16x16x32_bf16 v[28:31], v[132:135], v[208:211], v[28:31]
	v_mfma_f32_16x16x32_bf16 v[24:27], v[140:143], v[208:211], v[24:27]
	v_mfma_f32_16x16x32_bf16 v[12:15], v[132:135], v[216:219], v[12:15]
	v_mfma_f32_16x16x32_bf16 v[8:11], v[140:143], v[216:219], v[8:11]
	s_setprio 0
	s_setprio 1
	v_mfma_f32_16x16x32_bf16 v[52:55], v[166:169], v[188:191], v[52:55]
	v_mfma_f32_16x16x32_bf16 v[48:51], v[180:183], v[188:191], v[48:51]
	v_mfma_f32_16x16x32_bf16 v[36:39], v[166:169], v[196:199], v[36:39]
	v_mfma_f32_16x16x32_bf16 v[32:35], v[180:183], v[196:199], v[32:35]
	v_mfma_f32_16x16x32_bf16 v[20:23], v[166:169], v[204:207], v[20:23]
	v_mfma_f32_16x16x32_bf16 v[16:19], v[180:183], v[204:207], v[16:19]
	v_mfma_f32_16x16x32_bf16 v[4:7], v[166:169], v[212:215], v[4:7]
	v_mfma_f32_16x16x32_bf16 v[0:3], v[180:183], v[212:215], v[0:3]
	v_mfma_f32_16x16x32_bf16 v[52:55], v[176:179], v[192:195], v[52:55]
	v_mfma_f32_16x16x32_bf16 v[48:51], v[184:187], v[192:195], v[48:51]
	v_mfma_f32_16x16x32_bf16 v[36:39], v[176:179], v[200:203], v[36:39]
	v_mfma_f32_16x16x32_bf16 v[32:35], v[184:187], v[200:203], v[32:35]
	v_mfma_f32_16x16x32_bf16 v[20:23], v[176:179], v[208:211], v[20:23]
	v_mfma_f32_16x16x32_bf16 v[16:19], v[184:187], v[208:211], v[16:19]
	v_mfma_f32_16x16x32_bf16 v[4:7], v[176:179], v[216:219], v[4:7]
	v_mfma_f32_16x16x32_bf16 v[0:3], v[184:187], v[216:219], v[0:3]
	s_setprio 0
	s_barrier
	s_add_u32 s0, s0, 0x100
	s_addc_u32 s1, s1, 0
	s_add_u32 s11, s11, 0x100
	s_addc_u32 s24, s24, 0
	s_cmp_ge_u32 s90, s60
	s_mov_b32 s2, s90
	s_cbranch_scc1 .LBB0_297

.LBB0_421:
	s_andn2_b64 vcc, exec, s[8:9]
	s_cbranch_vccnz .LBB0_285
	s_branch .LBB0_285
